# MLA variant 6: as variant 3 with the restaging block behind the second MFMA step
# speedup vs baseline: 1.0065x; 1.0065x over previous
.LBB0_190:
	s_bitcmp1_b32 s1, 0
	s_cselect_b32 s0, 0x7000, 0
	v_add_u32_e32 v100, s0, v174
	v_add3_u32 v185, s0, v192, v159
	v_add3_u32 v100, v100, v175, v176
	v_add_u32_e32 v184, v100, v177
	v_add_u32_e32 v183, v100, v178
	v_add_u32_e32 v182, v100, v179
	v_add_u32_e32 v181, v100, v180
	ds_read_b64_tr_b16 v[112:113], v184 offset:20480
	ds_read_b64_tr_b16 v[114:115], v184 offset:20992
	ds_read_b64_tr_b16 v[108:109], v183 offset:20480
	ds_read_b64_tr_b16 v[110:111], v183 offset:20992
	ds_read_b64_tr_b16 v[104:105], v182 offset:20480
	ds_read_b64_tr_b16 v[106:107], v182 offset:20992
	ds_read_b64_tr_b16 v[100:101], v181 offset:20480
	ds_read_b64_tr_b16 v[102:103], v181 offset:20992
	ds_read_b128 v[186:189], v185
	ds_read_b128 v[194:197], v185 offset:64
	ds_read_b128 v[202:205], v185 offset:128
	ds_read_b128 v[144:147], v185 offset:1280
	ds_read_b128 v[128:131], v185 offset:1344
	ds_read_b128 v[140:143], v185 offset:1408
	ds_read_b128 v[124:127], v185 offset:10240
	s_waitcnt lgkmcnt(6)
	v_mfma_f32_16x16x32_bf16 v[136:139], v[186:189], v[12:15], v[36:39]
	v_mfma_f32_16x16x32_bf16 v[120:123], v[186:189], v[20:23], v[48:51]
	ds_read_b128 v[186:189], v185 offset:10304
	s_waitcnt lgkmcnt(6)
	v_mfma_f32_16x16x32_bf16 v[136:139], v[194:197], v[16:19], v[136:139]
	v_mfma_f32_16x16x32_bf16 v[120:123], v[194:197], v[24:27], v[120:123]
	ds_read_b128 v[194:197], v185 offset:10368
	s_andn2_b32 s0, 1, s1
	s_mulk_i32 s0, 0x7000
	s_add_i32 s10, s1, 1
	v_add3_u32 v132, s0, v151, v155
	v_add3_u32 v133, s0, v157, v170
	v_add_u32_e32 v134, s0, v171
	s_waitcnt vmcnt(2)
	ds_write_b128 v132, v[8:11]
	v_add3_u32 v134, v134, v173, v172
	s_add_i32 s0, s1, 3
	s_min_u32 s0, s0, s83
	s_waitcnt vmcnt(0)
	ds_write_b128 v133, v[28:31]
	s_lshl_b32 s0, s0, 6
	ds_write_b128 v134, v[32:35] offset:20480
	v_add_u32_e32 v8, s0, v154
	v_add_u32_e32 v28, s0, v156
	s_add_i32 s0, s1, 2
	v_ashrrev_i32_e32 v9, 31, v8
	v_ashrrev_i32_e32 v29, 31, v28
	s_min_u32 s0, s0, s83
	v_lshlrev_b64 v[10:11], 11, v[8:9]
	v_lshlrev_b64 v[8:9], 6, v[8:9]
	v_lshlrev_b64 v[30:31], 11, v[28:29]
	v_lshlrev_b64 v[28:29], 6, v[28:29]
	v_lshl_add_u32 v32, s0, 6, v158
	v_lshl_add_u64 v[8:9], v[162:163], 0, v[8:9]
	v_lshl_add_u64 v[28:29], v[166:167], 0, v[28:29]
	v_ashrrev_i32_e32 v33, 31, v32
	v_lshl_add_u64 v[10:11], v[164:165], 0, v[10:11]
	v_lshl_add_u64 v[8:9], v[8:9], 0, s[58:59]
	v_lshl_add_u64 v[30:31], v[168:169], 0, v[30:31]
	v_lshl_add_u64 v[28:29], v[28:29], 0, s[58:59]
	v_lshlrev_b64 v[32:33], 11, v[32:33]
	v_cndmask_b32_e64 v9, v9, v11, s[6:7]
	v_cndmask_b32_e64 v8, v8, v10, s[6:7]
	v_cndmask_b32_e64 v29, v29, v31, s[8:9]
	v_cndmask_b32_e64 v28, v28, v30, s[8:9]
	v_lshl_add_u64 v[32:33], v[160:161], 0, v[32:33]
	global_load_dwordx4 v[8:11], v[8:9], off
	global_load_dwordx4 v[28:31], v[28:29], off
	global_load_dwordx4 v[32:35], v[32:33], off offset:128
	s_waitcnt lgkmcnt(9)
	v_mfma_f32_16x16x32_bf16 v[136:139], v[202:205], v[0:3], v[136:139]
	v_mfma_f32_16x16x32_bf16 v[120:123], v[202:205], v[4:7], v[120:123]
	ds_read_b128 v[202:205], v185 offset:11520
	s_waitcnt lgkmcnt(9)
	v_mfma_f32_16x16x32_bf16 v[132:135], v[144:147], v[12:15], v[36:39]
	v_mfma_f32_16x16x32_bf16 v[116:119], v[144:147], v[20:23], v[48:51]
	s_waitcnt lgkmcnt(8)
	v_mfma_f32_16x16x32_bf16 v[132:135], v[128:131], v[16:19], v[132:135]
	v_mfma_f32_16x16x32_bf16 v[116:119], v[128:131], v[24:27], v[116:119]
	s_waitcnt lgkmcnt(7)
	v_mfma_f32_16x16x32_bf16 v[132:135], v[140:143], v[0:3], v[132:135]
	v_mfma_f32_16x16x32_bf16 v[116:119], v[140:143], v[4:7], v[116:119]
	s_waitcnt lgkmcnt(6)
	v_mfma_f32_16x16x32_bf16 v[140:143], v[124:127], v[12:15], v[36:39]
	v_mfma_f32_16x16x32_bf16 v[124:127], v[124:127], v[20:23], v[48:51]
	s_waitcnt lgkmcnt(5)
	v_mfma_f32_16x16x32_bf16 v[140:143], v[186:189], v[16:19], v[140:143]
	v_mfma_f32_16x16x32_bf16 v[124:127], v[186:189], v[24:27], v[124:127]
	ds_read_b128 v[186:189], v185 offset:11584
	s_waitcnt lgkmcnt(5)
	v_mfma_f32_16x16x32_bf16 v[140:143], v[194:197], v[0:3], v[140:143]
	v_mfma_f32_16x16x32_bf16 v[124:127], v[194:197], v[4:7], v[124:127]
	ds_read_b128 v[194:197], v185 offset:11648
	s_waitcnt lgkmcnt(2)
	v_mfma_f32_16x16x32_bf16 v[144:147], v[202:205], v[12:15], v[36:39]
	v_mfma_f32_16x16x32_bf16 v[128:131], v[202:205], v[20:23], v[48:51]
	s_waitcnt lgkmcnt(1)
	v_mfma_f32_16x16x32_bf16 v[144:147], v[186:189], v[16:19], v[144:147]
	v_mfma_f32_16x16x32_bf16 v[128:131], v[186:189], v[24:27], v[128:131]
	s_waitcnt lgkmcnt(0)
	v_mfma_f32_16x16x32_bf16 v[144:147], v[194:197], v[0:3], v[144:147]
	v_mfma_f32_16x16x32_bf16 v[128:131], v[194:197], v[4:7], v[128:131]
	s_cmp_ge_u32 s10, s82
	s_cbranch_scc1 .LBB0_196
	s_cmp_lg_u32 s1, 0
	s_cselect_b64 s[0:1], -1, 0
	s_and_b32 s11, s10, 3
	s_cmp_lg_u32 s11, 0
	s_cselect_b64 s[14:15], -1, 0
	s_and_b64 s[0:1], s[0:1], s[14:15]
	s_and_b64 vcc, exec, s[0:1]
	s_cbranch_vccnz .LBB0_196
	v_max_f32_e32 v185, v137, v137
	v_max_f32_e32 v186, v136, v136
	v_max_f32_e32 v185, v186, v185
	v_max3_f32 v185, v185, v138, v139
	v_max3_f32 v185, v185, v132, v133
	v_max3_f32 v185, v185, v134, v135
	v_max3_f32 v185, v185, v140, v141
	v_max3_f32 v185, v185, v142, v143
	v_max3_f32 v185, v185, v144, v145
	v_max3_f32 v185, v185, v146, v147
	v_mov_b32_e32 v186, v185
	s_nop 1
	v_permlane16_swap_b32_e32 v185, v186
	v_max_f32_e32 v186, v186, v186
	v_max_f32_e32 v185, v185, v185
	v_max_f32_e32 v185, v185, v186
	v_mov_b32_e32 v186, v185
	s_nop 1
	v_permlane32_swap_b32_e32 v185, v186
	v_max_f32_e32 v186, v186, v186
	v_max_f32_e32 v185, v185, v185
	v_max_f32_e32 v185, v185, v186
	v_cmp_lt_f32_e32 vcc, s44, v185
	s_cbranch_vccz .LBB0_194
	s_nop 0
	v_cndmask_b32_e32 v185, 0, v185, vcc
	v_exp_f32_e64 v186, -v185
	v_lshlrev_b32_e32 v188, 16, v56
	v_and_b32_e32 v189, 0xffff0000, v56
	v_sub_f32_e32 v139, v139, v185
	v_pk_mul_f32 v[188:189], v[186:187], v[188:189] op_sel_hi:[0,1]
	v_cvt_pk_bf16_f32 v56, v188, v189
	v_lshlrev_b32_e32 v188, 16, v57
	v_and_b32_e32 v189, 0xffff0000, v57
	v_pk_mul_f32 v[188:189], v[186:187], v[188:189] op_sel_hi:[0,1]
	v_cvt_pk_bf16_f32 v57, v188, v189
	v_lshlrev_b32_e32 v188, 16, v58
	v_and_b32_e32 v189, 0xffff0000, v58
	v_pk_mul_f32 v[188:189], v[186:187], v[188:189] op_sel_hi:[0,1]
	v_cvt_pk_bf16_f32 v58, v188, v189
	v_lshlrev_b32_e32 v188, 16, v59
	v_and_b32_e32 v189, 0xffff0000, v59
	v_pk_mul_f32 v[188:189], v[186:187], v[188:189] op_sel_hi:[0,1]
	v_cvt_pk_bf16_f32 v59, v188, v189
	v_lshlrev_b32_e32 v188, 16, v52
	v_and_b32_e32 v189, 0xffff0000, v52
	v_pk_mul_f32 v[188:189], v[186:187], v[188:189] op_sel_hi:[0,1]
	v_cvt_pk_bf16_f32 v52, v188, v189
	v_lshlrev_b32_e32 v188, 16, v53
	v_and_b32_e32 v189, 0xffff0000, v53
	v_pk_mul_f32 v[188:189], v[186:187], v[188:189] op_sel_hi:[0,1]
	v_cvt_pk_bf16_f32 v53, v188, v189
	v_lshlrev_b32_e32 v188, 16, v54
	v_and_b32_e32 v189, 0xffff0000, v54
	v_pk_mul_f32 v[188:189], v[186:187], v[188:189] op_sel_hi:[0,1]
	v_cvt_pk_bf16_f32 v54, v188, v189
	v_lshlrev_b32_e32 v188, 16, v55
	v_and_b32_e32 v189, 0xffff0000, v55
	v_pk_mul_f32 v[78:79], v[78:79], v[186:187] op_sel_hi:[1,0]
	v_pk_mul_f32 v[76:77], v[76:77], v[186:187] op_sel_hi:[1,0]
	v_pk_mul_f32 v[98:99], v[98:99], v[186:187] op_sel_hi:[1,0]
	v_pk_mul_f32 v[96:97], v[96:97], v[186:187] op_sel_hi:[1,0]
	v_pk_mul_f32 v[94:95], v[94:95], v[186:187] op_sel_hi:[1,0]
	v_pk_mul_f32 v[92:93], v[92:93], v[186:187] op_sel_hi:[1,0]
	v_pk_mul_f32 v[86:87], v[86:87], v[186:187] op_sel_hi:[1,0]
	v_pk_mul_f32 v[84:85], v[84:85], v[186:187] op_sel_hi:[1,0]
	v_pk_mul_f32 v[42:43], v[42:43], v[186:187] op_sel_hi:[1,0]
	v_pk_mul_f32 v[40:41], v[40:41], v[186:187] op_sel_hi:[1,0]
	v_pk_mul_f32 v[186:187], v[186:187], v[188:189] op_sel_hi:[0,1]
	v_sub_f32_e32 v138, v138, v185
	v_sub_f32_e32 v137, v137, v185
	v_sub_f32_e32 v136, v136, v185
	v_sub_f32_e32 v135, v135, v185
	v_sub_f32_e32 v134, v134, v185
	v_sub_f32_e32 v133, v133, v185
	v_sub_f32_e32 v132, v132, v185
	v_sub_f32_e32 v143, v143, v185
	v_sub_f32_e32 v142, v142, v185
	v_sub_f32_e32 v141, v141, v185
	v_sub_f32_e32 v140, v140, v185
	v_sub_f32_e32 v147, v147, v185
	v_sub_f32_e32 v146, v146, v185
	v_sub_f32_e32 v145, v145, v185
	v_sub_f32_e32 v144, v144, v185
	v_cvt_pk_bf16_f32 v55, v186, v187
	v_sub_f32_e32 v39, v39, v185
	v_sub_f32_e32 v38, v38, v185
	v_sub_f32_e32 v37, v37, v185
	v_sub_f32_e32 v36, v36, v185
